# v35_middpp
# baseline (speedup 1.0000x reference)
; __device__ __forceinline__ float bf_lo(unsigned w) { return __uint_as_float(w << 16); }
; __device__ __forceinline__ float bf_hi(unsigned w) { return __uint_as_float(w & 0xffff0000u); }
; __device__ __forceinline__ float wave_sum(float v) {
; #pragma unroll
;     for (int o = 1; o < 64; o <<= 1) v += __shfl_xor(v, o);
;     return v;
; __device__ __forceinline__ void phase_mid(const Params& p, int gw, int NGW, int lane) {
;     ...
;     for (int row = gw; row < MT; row += NGW) {
;         const float r1 = rsqrtf(wave_sum(SSQ[(size_t)lane * MT + row]) * (1.f / DM) + EPSN);
;         const u32x2* mr = (const u32x2*)(MO + (size_t)row * DM) + lane; const f32x4* xr = (const f32x4*)(x + (size_t)row * DM) + lane;
;         const f32x4* g1p = g1 + lane; const f32x4* g2p = g2 + lane;
;         asm volatile("" : "+v"(g1p), "+v"(g2p), "+v"(mr), "+v"(xr));
;         f32x4 h[16]; float ss = 0.f;
; #pragma unroll
;         for (int j = 0; j < 16; ++j) { const u32x2 mw = mr[64 * j]; const f32x4 mo = {bf_lo(mw.x), bf_hi(mw.x), bf_lo(mw.y), bf_hi(mw.y)}; h[j] = xr[64 * j] + mo * r1 * g1p[64 * j]; ss += (h[j][0] * h[j][0] + h[j][1] * h[j][1]) + (h[j][2] * h[j][2] + h[j][3] * h[j][3]); }
.LBB0_711:
	global_load_dword v26, v[10:11], off
	v_lshl_add_u64 v[20:21], v[0:1], 0, s[6:7]
	v_mov_b64_e32 v[14:15], v[4:5]
	v_mov_b64_e32 v[18:19], v[12:13]
	v_mov_b64_e32 v[16:17], v[2:3]
	flat_load_dwordx4 v[28:31], v[18:19]
	flat_load_dwordx4 v[32:35], v[18:19] offset:1024
	flat_load_dwordx4 v[36:39], v[16:17]
	flat_load_dwordx4 v[40:43], v[16:17] offset:1024
	flat_load_dwordx2 v[66:67], v[20:21]
	flat_load_dwordx2 v[68:69], v[20:21] offset:512
	flat_load_dwordx2 v[70:71], v[20:21] offset:1024
	flat_load_dwordx2 v[72:73], v[20:21] offset:1536
	flat_load_dwordx4 v[46:49], v[18:19] offset:2048
	flat_load_dwordx4 v[50:53], v[18:19] offset:3072
	flat_load_dwordx4 v[54:57], v[16:17] offset:2048
	flat_load_dwordx4 v[58:61], v[16:17] offset:3072
	v_add_co_u32_e32 v92, vcc, s9, v18
	flat_load_dwordx2 v[168:169], v[20:21] offset:2048
	flat_load_dwordx2 v[170:171], v[20:21] offset:2560
	flat_load_dwordx2 v[172:173], v[20:21] offset:3072
	flat_load_dwordx2 v[180:181], v[20:21] offset:3584
	v_addc_co_u32_e32 v93, vcc, 0, v19, vcc
	v_add_co_u32_e32 v100, vcc, s9, v16
	v_lshl_add_u64 v[24:25], v[6:7], 0, s[6:7]
	s_nop 0
	v_addc_co_u32_e32 v101, vcc, 0, v17, vcc
	v_add_co_u32_e32 v20, vcc, s9, v20
	v_lshl_add_u64 v[22:23], v[8:9], 0, s[6:7]
	s_nop 0
	v_addc_co_u32_e32 v21, vcc, 0, v21, vcc
	v_add_co_u32_e32 v124, vcc, s3, v18
	s_add_i32 s17, s17, s60
	s_nop 0
	v_addc_co_u32_e32 v125, vcc, 0, v19, vcc
	v_add_co_u32_e32 v132, vcc, s3, v16
	s_add_u32 s6, s6, s12
	s_nop 0
	v_addc_co_u32_e32 v133, vcc, 0, v17, vcc
	v_add_co_u32_e32 v156, vcc, s16, v18
	s_addc_u32 s7, s7, s13
	s_nop 0
	v_addc_co_u32_e32 v157, vcc, 0, v19, vcc
	v_add_co_u32_e32 v164, vcc, s16, v16
	v_lshl_add_u64 v[10:11], v[10:11], 0, s[4:5]
	s_nop 0
	v_addc_co_u32_e32 v165, vcc, 0, v17, vcc
	flat_load_dwordx2 v[182:183], v[20:21]
	flat_load_dwordx2 v[184:185], v[20:21] offset:512
	flat_load_dwordx2 v[186:187], v[20:21] offset:1024
	flat_load_dwordx2 v[188:189], v[20:21] offset:1536
	flat_load_dwordx2 v[190:191], v[20:21] offset:2048
	flat_load_dwordx2 v[194:195], v[20:21] offset:2560
	flat_load_dwordx4 v[16:19], v[92:93]
	flat_load_dwordx4 v[80:83], v[92:93] offset:1024
	flat_load_dwordx4 v[62:65], v[100:101]
	flat_load_dwordx4 v[84:87], v[100:101] offset:1024
	flat_load_dwordx2 v[196:197], v[20:21] offset:3072
	flat_load_dwordx4 v[88:91], v[92:93] offset:2048
	s_nop 0
	flat_load_dwordx4 v[92:95], v[92:93] offset:3072
	s_nop 0
	flat_load_dwordx2 v[20:21], v[20:21] offset:3584
	s_nop 0
	flat_load_dwordx4 v[96:99], v[100:101] offset:2048
	s_nop 0
	flat_load_dwordx4 v[100:103], v[100:101] offset:3072
	s_nop 0
	flat_load_dwordx4 v[104:107], v[124:125]
	flat_load_dwordx4 v[108:111], v[124:125] offset:1024
	flat_load_dwordx4 v[112:115], v[132:133]
	flat_load_dwordx4 v[116:119], v[132:133] offset:1024
	flat_load_dwordx4 v[120:123], v[124:125] offset:2048
	s_nop 0
	flat_load_dwordx4 v[124:127], v[124:125] offset:3072
	s_nop 0
	flat_load_dwordx4 v[128:131], v[132:133] offset:2048
	s_nop 0
	flat_load_dwordx4 v[132:135], v[132:133] offset:3072
	s_nop 0
	flat_load_dwordx4 v[136:139], v[156:157]
	flat_load_dwordx4 v[140:143], v[156:157] offset:1024
	flat_load_dwordx4 v[144:147], v[164:165]
	flat_load_dwordx4 v[148:151], v[164:165] offset:1024
	flat_load_dwordx4 v[152:155], v[156:157] offset:2048
	s_nop 0
	flat_load_dwordx4 v[156:159], v[156:157] offset:3072
	s_nop 0
	flat_load_dwordx4 v[160:163], v[164:165] offset:2048
	s_nop 0
	flat_load_dwordx4 v[164:167], v[164:165] offset:3072
	v_lshl_add_u64 v[12:13], v[12:13], 0, s[14:15]
	s_cmpk_lt_i32 s17, 0x2000
	s_waitcnt vmcnt(0) lgkmcnt(0)
	v_lshlrev_b32_e32 v198, 16, v66
	ds_bpermute_b32 v27, v45, v26
	v_and_b32_e32 v199, 0xffff0000, v66
	v_lshlrev_b32_e32 v66, 16, v67
	v_and_b32_e32 v67, 0xffff0000, v67
	v_lshlrev_b32_e32 v200, 16, v68
	s_waitcnt lgkmcnt(0)
	v_add_f32_e32 v26, v26, v27
	ds_bpermute_b32 v27, v74, v26
	v_and_b32_e32 v201, 0xffff0000, v68
	v_lshlrev_b32_e32 v68, 16, v69
	v_and_b32_e32 v69, 0xffff0000, v69
	v_lshlrev_b32_e32 v202, 16, v70
	s_waitcnt lgkmcnt(0)
	v_add_f32_e32 v26, v26, v27
	ds_bpermute_b32 v27, v75, v26
	v_and_b32_e32 v203, 0xffff0000, v70
	v_lshlrev_b32_e32 v70, 16, v71
	v_and_b32_e32 v71, 0xffff0000, v71
	v_lshlrev_b32_e32 v204, 16, v72
	s_waitcnt lgkmcnt(0)
	v_add_f32_e32 v26, v26, v27
	ds_bpermute_b32 v27, v76, v26
	v_and_b32_e32 v205, 0xffff0000, v72
	v_lshlrev_b32_e32 v72, 16, v73
	v_and_b32_e32 v73, 0xffff0000, v73
	v_lshlrev_b32_e32 v206, 16, v168
	s_waitcnt lgkmcnt(0)
	v_add_f32_e32 v26, v26, v27
	ds_bpermute_b32 v27, v77, v26
	v_and_b32_e32 v207, 0xffff0000, v168
	v_lshlrev_b32_e32 v168, 16, v169
	v_and_b32_e32 v169, 0xffff0000, v169
	v_lshlrev_b32_e32 v208, 16, v170
	s_waitcnt lgkmcnt(0)
	v_add_f32_e32 v26, v26, v27
	ds_bpermute_b32 v27, v78, v26
	v_and_b32_e32 v209, 0xffff0000, v170
	v_lshlrev_b32_e32 v170, 16, v171
	v_and_b32_e32 v171, 0xffff0000, v171
	v_lshlrev_b32_e32 v212, 16, v180
	s_waitcnt lgkmcnt(0)
; __device__ __forceinline__ float bf_lo(unsigned w) { return __uint_as_float(w << 16); }
; __device__ __forceinline__ float bf_hi(unsigned w) { return __uint_as_float(w & 0xffff0000u); }
; __device__ __forceinline__ void phase_mid(const Params& p, int gw, int NGW, int lane) {
;     ...
;         const float r1 = rsqrtf(wave_sum(SSQ[(size_t)lane * MT + row]) * (1.f / DM) + EPSN);
;         const u32x2* mr = (const u32x2*)(MO + (size_t)row * DM) + lane; const f32x4* xr = (const f32x4*)(x + (size_t)row * DM) + lane;
;         const f32x4* g1p = g1 + lane; const f32x4* g2p = g2 + lane;
;         asm volatile("" : "+v"(g1p), "+v"(g2p), "+v"(mr), "+v"(xr));
;         f32x4 h[16]; float ss = 0.f;
; #pragma unroll
;         for (int j = 0; j < 16; ++j) { const u32x2 mw = mr[64 * j]; const f32x4 mo = {bf_lo(mw.x), bf_hi(mw.x), bf_lo(mw.y), bf_hi(mw.y)}; h[j] = xr[64 * j] + mo * r1 * g1p[64 * j]; ss += (h[j][0] * h[j][0] + h[j][1] * h[j][1]) + (h[j][2] * h[j][2] + h[j][3] * h[j][3]); }
	v_add_f32_e32 v26, v26, v27
	v_fmamk_f32 v26, v26, 0x39800000, v79
	v_mul_f32_e32 v27, 0x4b800000, v26
	v_cmp_gt_f32_e32 vcc, s8, v26
	v_and_b32_e32 v213, 0xffff0000, v180
	v_lshlrev_b32_e32 v180, 16, v181
	v_cndmask_b32_e32 v26, v26, v27, vcc
	v_rsq_f32_e32 v26, v26
	v_and_b32_e32 v181, 0xffff0000, v181
	v_lshlrev_b32_e32 v214, 16, v182
	v_and_b32_e32 v215, 0xffff0000, v182
	v_mul_f32_e32 v27, 0x45800000, v26
	v_cndmask_b32_e32 v26, v26, v27, vcc
	v_lshlrev_b32_e32 v182, 16, v183
	v_and_b32_e32 v183, 0xffff0000, v183
	v_lshlrev_b32_e32 v218, 16, v186
	v_and_b32_e32 v219, 0xffff0000, v186
	v_lshlrev_b32_e32 v186, 16, v187
	v_and_b32_e32 v187, 0xffff0000, v187
	v_lshlrev_b32_e32 v220, 16, v188
	v_and_b32_e32 v221, 0xffff0000, v188
	v_lshlrev_b32_e32 v188, 16, v189
	v_and_b32_e32 v189, 0xffff0000, v189
	v_lshlrev_b32_e32 v224, 16, v194
	v_and_b32_e32 v225, 0xffff0000, v194
	v_lshlrev_b32_e32 v194, 16, v195
	v_and_b32_e32 v195, 0xffff0000, v195
	v_lshlrev_b32_e32 v226, 16, v196
	v_and_b32_e32 v227, 0xffff0000, v196
	v_lshlrev_b32_e32 v196, 16, v197
	v_and_b32_e32 v197, 0xffff0000, v197
	v_pk_mul_f32 v[198:199], v[26:27], v[198:199] op_sel_hi:[0,1]
	v_pk_mul_f32 v[66:67], v[26:27], v[66:67] op_sel_hi:[0,1]
	v_pk_mul_f32 v[200:201], v[26:27], v[200:201] op_sel_hi:[0,1]
	v_pk_mul_f32 v[68:69], v[26:27], v[68:69] op_sel_hi:[0,1]
	v_lshlrev_b32_e32 v210, 16, v172
	v_and_b32_e32 v211, 0xffff0000, v172
	v_lshlrev_b32_e32 v172, 16, v173
	v_and_b32_e32 v173, 0xffff0000, v173
	v_lshlrev_b32_e32 v216, 16, v184
	v_and_b32_e32 v217, 0xffff0000, v184
	v_lshlrev_b32_e32 v184, 16, v185
	v_and_b32_e32 v185, 0xffff0000, v185
	v_lshlrev_b32_e32 v222, 16, v190
	v_and_b32_e32 v223, 0xffff0000, v190
	v_lshlrev_b32_e32 v190, 16, v191
	v_and_b32_e32 v191, 0xffff0000, v191
	v_lshlrev_b32_e32 v228, 16, v20
	v_and_b32_e32 v229, 0xffff0000, v20
	v_lshlrev_b32_e32 v20, 16, v21
	v_and_b32_e32 v21, 0xffff0000, v21
	v_pk_mul_f32 v[202:203], v[26:27], v[202:203] op_sel_hi:[0,1]
	v_pk_mul_f32 v[70:71], v[26:27], v[70:71] op_sel_hi:[0,1]
	v_pk_mul_f32 v[204:205], v[26:27], v[204:205] op_sel_hi:[0,1]
	v_pk_mul_f32 v[72:73], v[26:27], v[72:73] op_sel_hi:[0,1]
	v_pk_mul_f32 v[206:207], v[26:27], v[206:207] op_sel_hi:[0,1]
	v_pk_mul_f32 v[168:169], v[26:27], v[168:169] op_sel_hi:[0,1]
	v_pk_mul_f32 v[208:209], v[26:27], v[208:209] op_sel_hi:[0,1]
	v_pk_mul_f32 v[170:171], v[26:27], v[170:171] op_sel_hi:[0,1]
	v_pk_mul_f32 v[212:213], v[26:27], v[212:213] op_sel_hi:[0,1]
	v_pk_mul_f32 v[180:181], v[26:27], v[180:181] op_sel_hi:[0,1]
	v_pk_mul_f32 v[214:215], v[26:27], v[214:215] op_sel_hi:[0,1]
	v_pk_mul_f32 v[182:183], v[26:27], v[182:183] op_sel_hi:[0,1]
	v_pk_mul_f32 v[218:219], v[26:27], v[218:219] op_sel_hi:[0,1]
	v_pk_mul_f32 v[186:187], v[26:27], v[186:187] op_sel_hi:[0,1]
	v_pk_mul_f32 v[220:221], v[26:27], v[220:221] op_sel_hi:[0,1]
	v_pk_mul_f32 v[188:189], v[26:27], v[188:189] op_sel_hi:[0,1]
	v_pk_mul_f32 v[224:225], v[26:27], v[224:225] op_sel_hi:[0,1]
	v_pk_mul_f32 v[194:195], v[26:27], v[194:195] op_sel_hi:[0,1]
	v_pk_mul_f32 v[226:227], v[26:27], v[226:227] op_sel_hi:[0,1]
	v_pk_mul_f32 v[196:197], v[26:27], v[196:197] op_sel_hi:[0,1]
	v_pk_fma_f32 v[232:233], v[38:39], v[66:67], v[30:31]
	v_pk_fma_f32 v[198:199], v[36:37], v[198:199], v[28:29]
	v_pk_fma_f32 v[234:235], v[42:43], v[68:69], v[34:35]
	v_pk_fma_f32 v[200:201], v[40:41], v[200:201], v[32:33]
	v_pk_mul_f32 v[210:211], v[26:27], v[210:211] op_sel_hi:[0,1]
	v_pk_mul_f32 v[172:173], v[26:27], v[172:173] op_sel_hi:[0,1]
	v_pk_mul_f32 v[216:217], v[26:27], v[216:217] op_sel_hi:[0,1]
	v_pk_mul_f32 v[184:185], v[26:27], v[184:185] op_sel_hi:[0,1]
	v_pk_mul_f32 v[222:223], v[26:27], v[222:223] op_sel_hi:[0,1]
	v_pk_mul_f32 v[190:191], v[26:27], v[190:191] op_sel_hi:[0,1]
	v_pk_mul_f32 v[228:229], v[26:27], v[228:229] op_sel_hi:[0,1]
	v_pk_mul_f32 v[230:231], v[26:27], v[20:21] op_sel_hi:[0,1]
	v_pk_fma_f32 v[236:237], v[56:57], v[70:71], v[48:49]
	v_pk_fma_f32 v[202:203], v[54:55], v[202:203], v[46:47]
	v_pk_fma_f32 v[70:71], v[60:61], v[72:73], v[52:53]
	v_pk_fma_f32 v[72:73], v[58:59], v[204:205], v[50:51]
	v_pk_fma_f32 v[66:67], v[64:65], v[168:169], v[18:19]
	v_pk_fma_f32 v[68:69], v[62:63], v[206:207], v[16:17]
	v_pk_fma_f32 v[62:63], v[86:87], v[170:171], v[82:83]
	v_pk_fma_f32 v[64:65], v[84:85], v[208:209], v[80:81]
	v_pk_fma_f32 v[54:55], v[102:103], v[180:181], v[94:95]
	v_pk_fma_f32 v[56:57], v[100:101], v[212:213], v[92:93]
	v_pk_fma_f32 v[50:51], v[114:115], v[182:183], v[106:107]
	v_pk_fma_f32 v[52:53], v[112:113], v[214:215], v[104:105]
	v_pk_fma_f32 v[40:41], v[130:131], v[186:187], v[122:123]
	v_pk_fma_f32 v[42:43], v[128:129], v[218:219], v[120:121]
	v_pk_fma_f32 v[36:37], v[134:135], v[188:189], v[126:127]
	v_pk_fma_f32 v[38:39], v[132:133], v[220:221], v[124:125]
	v_pk_fma_f32 v[28:29], v[150:151], v[194:195], v[142:143]
	v_pk_fma_f32 v[30:31], v[148:149], v[224:225], v[140:141]
	v_pk_fma_f32 v[20:21], v[162:163], v[196:197], v[154:155]
	v_pk_fma_f32 v[26:27], v[160:161], v[226:227], v[152:153]
	v_pk_mul_f32 v[80:81], v[232:233], v[232:233]
	v_pk_mul_f32 v[82:83], v[198:199], v[198:199]
	v_pk_mul_f32 v[84:85], v[234:235], v[234:235]
	v_pk_mul_f32 v[86:87], v[200:201], v[200:201]
	v_pk_fma_f32 v[58:59], v[98:99], v[172:173], v[90:91]
	v_pk_fma_f32 v[60:61], v[96:97], v[210:211], v[88:89]
	v_pk_fma_f32 v[46:47], v[118:119], v[184:185], v[110:111]
	v_pk_fma_f32 v[48:49], v[116:117], v[216:217], v[108:109]
	v_pk_mul_f32 v[90:91], v[66:67], v[66:67]
	v_pk_mul_f32 v[92:93], v[68:69], v[68:69]
	v_mul_f32_e32 v94, v65, v65
	v_mul_f32_e32 v96, v63, v63
	v_pk_mul_f32 v[98:99], v[54:55], v[54:55]
; __device__ __forceinline__ unsigned cvt_pk_bf16(float lo, float hi) { unsigned r; asm volatile("v_cvt_pk_bf16_f32 %0, %1, %2" : "=v"(r) : "v"(lo), "v"(hi)); return r; }
; __device__ __forceinline__ float bf_lo(unsigned w) { return __uint_as_float(w << 16); }
; __device__ __forceinline__ float bf_hi(unsigned w) { return __uint_as_float(w & 0xffff0000u); }
; __device__ __forceinline__ float wave_sum(float v) {
; #pragma unroll
;     for (int o = 1; o < 64; o <<= 1) v += __shfl_xor(v, o);
;     return v;
; __device__ __forceinline__ void phase_mid(const Params& p, int gw, int NGW, int lane) {
;     ...
;         for (int j = 0; j < 16; ++j) { const u32x2 mw = mr[64 * j]; const f32x4 mo = {bf_lo(mw.x), bf_hi(mw.x), bf_lo(mw.y), bf_hi(mw.y)}; h[j] = xr[64 * j] + mo * r1 * g1p[64 * j]; ss += (h[j][0] * h[j][0] + h[j][1] * h[j][1]) + (h[j][2] * h[j][2] + h[j][3] * h[j][3]); }
;         const float r2 = rsqrtf(wave_sum(ss) * (1.f / DM) + EPSN);
;         u32x2* ho = (u32x2*)(H1 + (size_t)row * DM) + lane; u32x2* co = (u32x2*)(Cb + (size_t)row * DM) + lane;
;         asm volatile("" : "+v"(ho), "+v"(co));
; #pragma unroll
;         for (int j = 0; j < 16; ++j) { { u32x2 hw; hw.x = cvt_pk_bf16(h[j][0], h[j][1]); hw.y = cvt_pk_bf16(h[j][2], h[j][3]); ho[64 * j] = hw; } const f32x4 c = h[j] * r2 * g2p[64 * j]; u32x2 w; w.x = cvt_pk_bf16(c[0], c[1]); w.y = cvt_pk_bf16(c[2], c[3]); co[64 * j] = w; }
	v_pk_mul_f32 v[100:101], v[56:57], v[56:57]
	v_mul_f32_e32 v102, v53, v53
	v_mul_f32_e32 v104, v51, v51
	v_pk_mul_f32 v[106:107], v[40:41], v[40:41]
	v_pk_mul_f32 v[108:109], v[42:43], v[42:43]
	v_mul_f32_e32 v110, v39, v39
	v_mul_f32_e32 v112, v37, v37
	v_pk_mul_f32 v[114:115], v[28:29], v[28:29]
	v_pk_mul_f32 v[116:117], v[30:31], v[30:31]
	v_mul_f32_e32 v118, v27, v27
	v_mul_f32_e32 v120, v21, v21
	v_cvt_pk_bf16_f32 v122, v198, v199
	v_cvt_pk_bf16_f32 v123, v232, v233
	v_pk_mov_b32 v[124:125], v[82:83], v[80:81] op_sel:[1,0]
	v_mov_b32_e32 v83, v81
	v_pk_mov_b32 v[80:81], v[86:87], v[84:85] op_sel:[1,0]
	v_mov_b32_e32 v87, v85
	global_store_dwordx2 v[24:25], v[122:123], off
	v_pk_mov_b32 v[126:127], v[92:93], v[90:91] op_sel:[1,0]
	v_mov_b32_e32 v93, v91
	v_pk_fma_f32 v[90:91], v[64:65], v[64:65], v[94:95] op_sel_hi:[1,1,0]
	v_pk_fma_f32 v[94:95], v[62:63], v[62:63], v[96:97] op_sel_hi:[1,1,0]
	v_pk_mov_b32 v[96:97], v[100:101], v[98:99] op_sel:[1,0]
	v_mov_b32_e32 v101, v99
	v_pk_fma_f32 v[98:99], v[52:53], v[52:53], v[102:103] op_sel_hi:[1,1,0]
	v_pk_fma_f32 v[102:103], v[50:51], v[50:51], v[104:105] op_sel_hi:[1,1,0]
	v_pk_mov_b32 v[104:105], v[108:109], v[106:107] op_sel:[1,0]
	v_mov_b32_e32 v109, v107
	v_pk_fma_f32 v[106:107], v[38:39], v[38:39], v[110:111] op_sel_hi:[1,1,0]
	v_pk_fma_f32 v[110:111], v[36:37], v[36:37], v[112:113] op_sel_hi:[1,1,0]
	v_pk_mov_b32 v[112:113], v[116:117], v[114:115] op_sel:[1,0]
	v_mov_b32_e32 v117, v115
	v_pk_fma_f32 v[114:115], v[26:27], v[26:27], v[118:119] op_sel_hi:[1,1,0]
	v_pk_fma_f32 v[118:119], v[20:21], v[20:21], v[120:121] op_sel_hi:[1,1,0]
	v_pk_add_f32 v[120:121], v[124:125], v[82:83]
	v_pk_add_f32 v[86:87], v[80:81], v[86:87]
	global_load_dwordx4 v[80:83], v176, s[24:25]
	global_load_dwordx4 v[122:125], v176, s[24:25] offset:1024
	global_load_dwordx4 v[148:151], v176, s[24:25] offset:2048
	global_load_dwordx4 v[152:155], v176, s[24:25] offset:3072
	v_add_u32_e32 v172, 0x1000, v176
	global_load_dwordx4 v[160:163], v172, s[24:25]
	global_load_dwordx4 v[168:171], v172, s[24:25] offset:1024
	global_load_dwordx4 v[180:183], v172, s[24:25] offset:2048
	global_load_dwordx4 v[184:187], v172, s[24:25] offset:3072
	v_add_u32_e32 v173, 0x2000, v176
	global_load_dwordx4 v[194:197], v173, s[24:25]
	global_load_dwordx4 v[204:207], v173, s[24:25] offset:1024
	global_load_dwordx4 v[208:211], v173, s[24:25] offset:2048
	global_load_dwordx4 v[212:215], v173, s[24:25] offset:3072
	v_add_u32_e32 v188, 0x3000, v176
	global_load_dwordx4 v[216:219], v188, s[24:25]
	global_load_dwordx4 v[224:227], v188, s[24:25] offset:1024
	global_load_dwordx4 v[238:241], v188, s[24:25] offset:2048
	global_load_dwordx4 v[242:245], v188, s[24:25] offset:3072
	v_mul_f32_e32 v44, v203, v203
	v_mul_f32_e32 v88, v237, v237
	v_mul_f32_e32 v128, v72, v72
	v_mul_f32_e32 v129, v73, v73
	v_mul_f32_e32 v130, v70, v70
	v_mul_f32_e32 v131, v71, v71
	v_pk_fma_f32 v[84:85], v[202:203], v[202:203], v[44:45] op_sel_hi:[1,1,0]
	v_pk_fma_f32 v[88:89], v[236:237], v[236:237], v[88:89] op_sel_hi:[1,1,0]
	v_pk_add_f32 v[96:97], v[96:97], v[100:101]
	v_pk_add_f32 v[100:101], v[104:105], v[108:109]
	v_pk_add_f32 v[108:109], v[120:121], v[120:121] op_sel:[0,1] op_sel_hi:[1,0]
	v_pk_add_f32 v[86:87], v[86:87], v[86:87] op_sel:[0,1] op_sel_hi:[1,0]
	v_mov_b32_e32 v85, v130
	v_mov_b32_e32 v89, v131
	v_mov_b32_e32 v109, v128
	v_mov_b32_e32 v87, v129
	v_pk_add_f32 v[84:85], v[84:85], v[88:89]
	v_pk_add_f32 v[86:87], v[108:109], v[86:87]
	v_pk_add_f32 v[92:93], v[126:127], v[92:93]
	v_pk_add_f32 v[84:85], v[86:87], v[84:85]
	v_mul_f32_e32 v132, v60, v60
	v_mul_f32_e32 v133, v61, v61
	v_mul_f32_e32 v134, v58, v58
	v_mul_f32_e32 v135, v59, v59
	v_pk_add_f32 v[88:89], v[92:93], v[92:93] op_sel:[0,1] op_sel_hi:[1,0]
	v_pk_add_f32 v[84:85], v[84:85], v[84:85] op_sel:[0,1] op_sel_hi:[1,0]
	v_mov_b32_e32 v91, v134
	v_mov_b32_e32 v95, v135
	v_mov_b32_e32 v89, v133
	v_mov_b32_e32 v85, v132
	v_pk_add_f32 v[90:91], v[90:91], v[94:95]
	v_pk_add_f32 v[84:85], v[84:85], v[88:89]
	v_pk_fma_f32 v[32:33], v[146:147], v[190:191], v[138:139]
	v_pk_add_f32 v[84:85], v[84:85], v[90:91]
	v_pk_fma_f32 v[34:35], v[144:145], v[222:223], v[136:137]
	v_mul_f32_e32 v136, v48, v48
	v_mul_f32_e32 v137, v49, v49
	v_mul_f32_e32 v138, v46, v46
	v_mul_f32_e32 v139, v47, v47
	v_pk_add_f32 v[92:93], v[96:97], v[96:97] op_sel:[0,1] op_sel_hi:[1,0]
	v_pk_add_f32 v[84:85], v[84:85], v[84:85] op_sel:[0,1] op_sel_hi:[1,0]
	v_mov_b32_e32 v99, v138
	v_mov_b32_e32 v103, v139
	v_mov_b32_e32 v93, v137
	v_mov_b32_e32 v85, v136
	v_pk_add_f32 v[94:95], v[98:99], v[102:103]
	v_pk_add_f32 v[84:85], v[84:85], v[92:93]
	v_mul_f32_e32 v140, v34, v34
	v_pk_add_f32 v[84:85], v[84:85], v[94:95]
	v_mul_f32_e32 v141, v35, v35
	v_mul_f32_e32 v142, v32, v32
	v_mul_f32_e32 v143, v33, v33
	v_pk_add_f32 v[96:97], v[100:101], v[100:101] op_sel:[0,1] op_sel_hi:[1,0]
	v_pk_add_f32 v[84:85], v[84:85], v[84:85] op_sel:[0,1] op_sel_hi:[1,0]
	v_mov_b32_e32 v107, v142
	v_mov_b32_e32 v111, v143
	v_mov_b32_e32 v97, v141
	v_mov_b32_e32 v85, v140
	v_pk_add_f32 v[98:99], v[106:107], v[110:111]
	v_pk_add_f32 v[84:85], v[84:85], v[96:97]
	v_pk_fma_f32 v[16:17], v[166:167], v[230:231], v[158:159]
	v_pk_fma_f32 v[18:19], v[164:165], v[228:229], v[156:157]
	v_pk_add_f32 v[104:105], v[112:113], v[116:117]
	v_pk_add_f32 v[84:85], v[84:85], v[98:99]
	v_mul_f32_e32 v144, v18, v18
	v_mul_f32_e32 v145, v19, v19
	v_mul_f32_e32 v146, v16, v16
	v_mul_f32_e32 v147, v17, v17
	v_pk_add_f32 v[100:101], v[104:105], v[104:105] op_sel:[0,1] op_sel_hi:[1,0]
	v_pk_add_f32 v[84:85], v[84:85], v[84:85] op_sel:[0,1] op_sel_hi:[1,0]
	v_mov_b32_e32 v115, v146
	v_mov_b32_e32 v119, v147
	v_mov_b32_e32 v101, v145
	v_mov_b32_e32 v85, v144
	v_pk_add_f32 v[102:103], v[114:115], v[118:119]
	v_pk_add_f32 v[84:85], v[84:85], v[100:101]
	s_nop 0
	v_pk_add_f32 v[84:85], v[84:85], v[102:103]
	s_nop 0
	v_add_f32_e32 v44, v84, v85
	s_nop 1
	v_add_f32_dpp v44, v44, v44 quad_perm:[1,0,3,2] row_mask:0xf bank_mask:0xf
	s_nop 1
	v_add_f32_dpp v44, v44, v44 quad_perm:[2,3,0,1] row_mask:0xf bank_mask:0xf
	s_nop 1
	v_add_f32_dpp v44, v44, v44 row_half_mirror row_mask:0xf bank_mask:0xf
	s_nop 1
	v_add_f32_dpp v44, v44, v44 row_mirror row_mask:0xf bank_mask:0xf
	s_nop 1
	v_add_f32_dpp v44, v44, v44 row_bcast:15 row_mask:0xa bank_mask:0xf
	s_nop 1
	v_add_f32_dpp v44, v44, v44 row_bcast:31 row_mask:0xc bank_mask:0xf
	s_nop 1
	v_readlane_b32 vcc_lo, v44, 63
	s_nop 1
	v_mov_b32_e32 v44, vcc_lo
	v_fmamk_f32 v44, v44, 0x39800000, v79
	v_mul_f32_e32 v84, 0x4b800000, v44
	v_cmp_gt_f32_e32 vcc, s8, v44
	s_nop 1
	v_cndmask_b32_e32 v44, v44, v84, vcc
	v_rsq_f32_e32 v44, v44
	s_nop 0
	v_mul_f32_e32 v84, 0x45800000, v44
	v_cndmask_b32_e32 v44, v44, v84, vcc
	v_pk_mul_f32 v[84:85], v[198:199], v[44:45] op_sel_hi:[1,0]
	v_pk_mul_f32 v[86:87], v[232:233], v[44:45] op_sel_hi:[1,0]
	s_waitcnt vmcnt(0)
; __device__ __forceinline__ unsigned cvt_pk_bf16(float lo, float hi) { unsigned r; asm volatile("v_cvt_pk_bf16_f32 %0, %1, %2" : "=v"(r) : "v"(lo), "v"(hi)); return r; }
; __device__ __forceinline__ void phase_mid(const Params& p, int gw, int NGW, int lane) {
;     ...
; #pragma unroll
;         for (int j = 0; j < 16; ++j) { { u32x2 hw; hw.x = cvt_pk_bf16(h[j][0], h[j][1]); hw.y = cvt_pk_bf16(h[j][2], h[j][3]); ho[64 * j] = hw; } const f32x4 c = h[j] * r2 * g2p[64 * j]; u32x2 w; w.x = cvt_pk_bf16(c[0], c[1]); w.y = cvt_pk_bf16(c[2], c[3]); co[64 * j] = w; }
	v_pk_mul_f32 v[80:81], v[80:81], v[84:85]
	v_pk_mul_f32 v[82:83], v[82:83], v[86:87]
	v_cvt_pk_bf16_f32 v80, v80, v81
	v_pk_mul_f32 v[84:85], v[200:201], v[44:45] op_sel_hi:[1,0]
	v_cvt_pk_bf16_f32 v81, v82, v83
	global_store_dwordx2 v[22:23], v[80:81], off
	v_cvt_pk_bf16_f32 v80, v200, v201
	v_cvt_pk_bf16_f32 v81, v234, v235
	global_store_dwordx2 v[24:25], v[80:81], off offset:512
	v_mov_b64_e32 v[80:81], v[122:123]
	v_mov_b64_e32 v[82:83], v[124:125]
	v_pk_mul_f32 v[86:87], v[234:235], v[44:45] op_sel_hi:[1,0]
	v_pk_mul_f32 v[80:81], v[80:81], v[84:85]
	v_pk_mul_f32 v[82:83], v[82:83], v[86:87]
	v_cvt_pk_bf16_f32 v80, v80, v81
	v_pk_mul_f32 v[84:85], v[202:203], v[44:45] op_sel_hi:[1,0]
	v_cvt_pk_bf16_f32 v81, v82, v83
	global_store_dwordx2 v[22:23], v[80:81], off offset:512
	v_cvt_pk_bf16_f32 v80, v202, v203
	v_cvt_pk_bf16_f32 v81, v236, v237
	global_store_dwordx2 v[24:25], v[80:81], off offset:1024
	v_mov_b64_e32 v[80:81], v[148:149]
	v_mov_b64_e32 v[82:83], v[150:151]
	v_pk_mul_f32 v[86:87], v[236:237], v[44:45] op_sel_hi:[1,0]
	v_pk_mul_f32 v[80:81], v[80:81], v[84:85]
	v_pk_mul_f32 v[82:83], v[82:83], v[86:87]
	v_cvt_pk_bf16_f32 v80, v80, v81
	v_add_co_u32_e32 v84, vcc, s9, v14
	v_cvt_pk_bf16_f32 v81, v82, v83
	global_store_dwordx2 v[22:23], v[80:81], off offset:1024
	v_cvt_pk_bf16_f32 v80, v72, v73
	v_cvt_pk_bf16_f32 v81, v70, v71
	global_store_dwordx2 v[24:25], v[80:81], off offset:1536
	v_mov_b64_e32 v[80:81], v[152:153]
	v_mov_b64_e32 v[82:83], v[154:155]
	v_pk_mul_f32 v[72:73], v[72:73], v[44:45] op_sel_hi:[1,0]
	v_pk_mul_f32 v[70:71], v[70:71], v[44:45] op_sel_hi:[1,0]
	v_addc_co_u32_e32 v85, vcc, 0, v15, vcc
	v_pk_mul_f32 v[70:71], v[70:71], v[82:83]
	v_pk_mul_f32 v[72:73], v[72:73], v[80:81]
	s_nop 0
	v_cvt_pk_bf16_f32 v72, v72, v73
	v_cvt_pk_bf16_f32 v73, v70, v71
	global_store_dwordx2 v[22:23], v[72:73], off offset:1536
	v_cvt_pk_bf16_f32 v70, v68, v69
	v_cvt_pk_bf16_f32 v71, v66, v67
	global_store_dwordx2 v[24:25], v[70:71], off offset:2048
	v_mov_b64_e32 v[70:71], v[160:161]
	v_mov_b64_e32 v[72:73], v[162:163]
	v_pk_mul_f32 v[68:69], v[68:69], v[44:45] op_sel_hi:[1,0]
	v_pk_mul_f32 v[66:67], v[66:67], v[44:45] op_sel_hi:[1,0]
	v_pk_mul_f32 v[68:69], v[68:69], v[70:71]
	v_pk_mul_f32 v[66:67], v[66:67], v[72:73]
	v_cvt_pk_bf16_f32 v68, v68, v69
	s_nop 0
	v_cvt_pk_bf16_f32 v69, v66, v67
	global_store_dwordx2 v[22:23], v[68:69], off offset:2048
	v_cvt_pk_bf16_f32 v66, v64, v65
	v_cvt_pk_bf16_f32 v67, v62, v63
	global_store_dwordx2 v[24:25], v[66:67], off offset:2560
	v_mov_b64_e32 v[66:67], v[168:169]
	v_mov_b64_e32 v[68:69], v[170:171]
	v_pk_mul_f32 v[64:65], v[64:65], v[44:45] op_sel_hi:[1,0]
	v_pk_mul_f32 v[62:63], v[62:63], v[44:45] op_sel_hi:[1,0]
	v_pk_mul_f32 v[64:65], v[64:65], v[66:67]
	v_pk_mul_f32 v[62:63], v[62:63], v[68:69]
	v_cvt_pk_bf16_f32 v64, v64, v65
	s_nop 0
	v_cvt_pk_bf16_f32 v65, v62, v63
	global_store_dwordx2 v[22:23], v[64:65], off offset:2560
	v_cvt_pk_bf16_f32 v62, v60, v61
	v_cvt_pk_bf16_f32 v63, v58, v59
	global_store_dwordx2 v[24:25], v[62:63], off offset:3072
	v_mov_b64_e32 v[62:63], v[180:181]
	v_mov_b64_e32 v[64:65], v[182:183]
	v_pk_mul_f32 v[60:61], v[60:61], v[44:45] op_sel_hi:[1,0]
	v_pk_mul_f32 v[58:59], v[58:59], v[44:45] op_sel_hi:[1,0]
	v_pk_mul_f32 v[60:61], v[60:61], v[62:63]
	v_pk_mul_f32 v[58:59], v[58:59], v[64:65]
	v_cvt_pk_bf16_f32 v60, v60, v61
	v_add_co_u32_e32 v62, vcc, s3, v14
	v_cvt_pk_bf16_f32 v61, v58, v59
	global_store_dwordx2 v[22:23], v[60:61], off offset:3072
	v_cvt_pk_bf16_f32 v58, v56, v57
	v_cvt_pk_bf16_f32 v59, v54, v55
	global_store_dwordx2 v[24:25], v[58:59], off offset:3584
	v_mov_b64_e32 v[58:59], v[184:185]
	v_mov_b64_e32 v[60:61], v[186:187]
	v_addc_co_u32_e32 v63, vcc, 0, v15, vcc
	v_add_co_u32_e32 v64, vcc, s9, v24
	v_pk_mul_f32 v[54:55], v[54:55], v[44:45] op_sel_hi:[1,0]
	s_nop 0
	v_addc_co_u32_e32 v65, vcc, 0, v25, vcc
	v_pk_mul_f32 v[24:25], v[56:57], v[44:45] op_sel_hi:[1,0]
	v_pk_mul_f32 v[54:55], v[54:55], v[60:61]
	v_pk_mul_f32 v[24:25], v[24:25], v[58:59]
	v_add_co_u32_e32 v58, vcc, s9, v22
	v_cvt_pk_bf16_f32 v24, v24, v25
	v_cvt_pk_bf16_f32 v25, v54, v55
	global_store_dwordx2 v[22:23], v[24:25], off offset:3584
	v_cvt_pk_bf16_f32 v24, v52, v53
	v_cvt_pk_bf16_f32 v25, v50, v51
	global_store_dwordx2 v[64:65], v[24:25], off
; __device__ __forceinline__ unsigned cvt_pk_bf16(float lo, float hi) { unsigned r; asm volatile("v_cvt_pk_bf16_f32 %0, %1, %2" : "=v"(r) : "v"(lo), "v"(hi)); return r; }
; __device__ __forceinline__ void phase_mid(const Params& p, int gw, int NGW, int lane) {
;     ...
; #pragma unroll
;         for (int j = 0; j < 16; ++j) { { u32x2 hw; hw.x = cvt_pk_bf16(h[j][0], h[j][1]); hw.y = cvt_pk_bf16(h[j][2], h[j][3]); ho[64 * j] = hw; } const f32x4 c = h[j] * r2 * g2p[64 * j]; u32x2 w; w.x = cvt_pk_bf16(c[0], c[1]); w.y = cvt_pk_bf16(c[2], c[3]); co[64 * j] = w; }
;     }
	v_mov_b64_e32 v[54:55], v[194:195]
	v_mov_b64_e32 v[56:57], v[196:197]
	v_addc_co_u32_e32 v59, vcc, 0, v23, vcc
	v_pk_mul_f32 v[22:23], v[52:53], v[44:45] op_sel_hi:[1,0]
	v_pk_mul_f32 v[24:25], v[50:51], v[44:45] op_sel_hi:[1,0]
	v_add_co_u32_e32 v14, vcc, s16, v14
	v_pk_mul_f32 v[22:23], v[22:23], v[54:55]
	v_pk_mul_f32 v[24:25], v[24:25], v[56:57]
	v_cvt_pk_bf16_f32 v22, v22, v23
	v_addc_co_u32_e32 v15, vcc, 0, v15, vcc
	v_cvt_pk_bf16_f32 v23, v24, v25
	global_store_dwordx2 v[58:59], v[22:23], off
	v_cvt_pk_bf16_f32 v22, v48, v49
	v_cvt_pk_bf16_f32 v23, v46, v47
	global_store_dwordx2 v[64:65], v[22:23], off offset:512
	v_mov_b64_e32 v[22:23], v[204:205]
	v_mov_b64_e32 v[24:25], v[206:207]
	v_pk_mul_f32 v[48:49], v[48:49], v[44:45] op_sel_hi:[1,0]
	v_pk_mul_f32 v[46:47], v[46:47], v[44:45] op_sel_hi:[1,0]
	v_pk_mul_f32 v[22:23], v[48:49], v[22:23]
	v_pk_mul_f32 v[24:25], v[46:47], v[24:25]
	v_cvt_pk_bf16_f32 v22, v22, v23
	s_nop 0
	v_cvt_pk_bf16_f32 v23, v24, v25
	global_store_dwordx2 v[58:59], v[22:23], off offset:512
	v_cvt_pk_bf16_f32 v22, v42, v43
	v_cvt_pk_bf16_f32 v23, v40, v41
	global_store_dwordx2 v[64:65], v[22:23], off offset:1024
	v_mov_b64_e32 v[22:23], v[208:209]
	v_mov_b64_e32 v[24:25], v[210:211]
	v_pk_mul_f32 v[42:43], v[42:43], v[44:45] op_sel_hi:[1,0]
	v_pk_mul_f32 v[40:41], v[40:41], v[44:45] op_sel_hi:[1,0]
	v_pk_mul_f32 v[22:23], v[42:43], v[22:23]
	v_pk_mul_f32 v[24:25], v[40:41], v[24:25]
	v_cvt_pk_bf16_f32 v22, v22, v23
	s_nop 0
	v_cvt_pk_bf16_f32 v23, v24, v25
	global_store_dwordx2 v[58:59], v[22:23], off offset:1024
	v_cvt_pk_bf16_f32 v22, v38, v39
	v_cvt_pk_bf16_f32 v23, v36, v37
	global_store_dwordx2 v[64:65], v[22:23], off offset:1536
	v_mov_b64_e32 v[22:23], v[212:213]
	v_mov_b64_e32 v[24:25], v[214:215]
	v_pk_mul_f32 v[38:39], v[38:39], v[44:45] op_sel_hi:[1,0]
	v_pk_mul_f32 v[36:37], v[36:37], v[44:45] op_sel_hi:[1,0]
	v_pk_mul_f32 v[22:23], v[38:39], v[22:23]
	v_pk_mul_f32 v[24:25], v[36:37], v[24:25]
	v_cvt_pk_bf16_f32 v22, v22, v23
	s_nop 0
	v_cvt_pk_bf16_f32 v23, v24, v25
	global_store_dwordx2 v[58:59], v[22:23], off offset:1536
	v_cvt_pk_bf16_f32 v22, v34, v35
	v_cvt_pk_bf16_f32 v23, v32, v33
	global_store_dwordx2 v[64:65], v[22:23], off offset:2048
	v_mov_b64_e32 v[22:23], v[216:217]
	v_mov_b64_e32 v[24:25], v[218:219]
	v_pk_mul_f32 v[34:35], v[34:35], v[44:45] op_sel_hi:[1,0]
	v_pk_mul_f32 v[32:33], v[32:33], v[44:45] op_sel_hi:[1,0]
	v_pk_mul_f32 v[22:23], v[34:35], v[22:23]
	v_pk_mul_f32 v[24:25], v[32:33], v[24:25]
	v_cvt_pk_bf16_f32 v22, v22, v23
	s_nop 0
	v_cvt_pk_bf16_f32 v23, v24, v25
	global_store_dwordx2 v[58:59], v[22:23], off offset:2048
	v_cvt_pk_bf16_f32 v22, v30, v31
	v_cvt_pk_bf16_f32 v23, v28, v29
	global_store_dwordx2 v[64:65], v[22:23], off offset:2560
	v_mov_b64_e32 v[22:23], v[224:225]
	v_mov_b64_e32 v[24:25], v[226:227]
	v_pk_mul_f32 v[30:31], v[30:31], v[44:45] op_sel_hi:[1,0]
	v_pk_mul_f32 v[28:29], v[28:29], v[44:45] op_sel_hi:[1,0]
	v_pk_mul_f32 v[22:23], v[30:31], v[22:23]
	v_pk_mul_f32 v[24:25], v[28:29], v[24:25]
	v_cvt_pk_bf16_f32 v22, v22, v23
	s_nop 0
	v_cvt_pk_bf16_f32 v23, v24, v25
	global_store_dwordx2 v[58:59], v[22:23], off offset:2560
	v_cvt_pk_bf16_f32 v22, v26, v27
	v_cvt_pk_bf16_f32 v23, v20, v21
	global_store_dwordx2 v[64:65], v[22:23], off offset:3072
	v_mov_b64_e32 v[22:23], v[238:239]
	v_mov_b64_e32 v[24:25], v[240:241]
	v_pk_mul_f32 v[26:27], v[26:27], v[44:45] op_sel_hi:[1,0]
	v_pk_mul_f32 v[20:21], v[20:21], v[44:45] op_sel_hi:[1,0]
	v_pk_mul_f32 v[22:23], v[26:27], v[22:23]
	v_pk_mul_f32 v[20:21], v[20:21], v[24:25]
	v_cvt_pk_bf16_f32 v22, v22, v23
	s_nop 0
	v_cvt_pk_bf16_f32 v23, v20, v21
	global_store_dwordx2 v[58:59], v[22:23], off offset:3072
	v_cvt_pk_bf16_f32 v20, v18, v19
	v_cvt_pk_bf16_f32 v21, v16, v17
	global_store_dwordx2 v[64:65], v[20:21], off offset:3584
	v_mov_b64_e32 v[20:21], v[242:243]
	v_mov_b64_e32 v[22:23], v[244:245]
	v_pk_mul_f32 v[14:15], v[18:19], v[44:45] op_sel_hi:[1,0]
	v_pk_mul_f32 v[16:17], v[16:17], v[44:45] op_sel_hi:[1,0]
	v_pk_mul_f32 v[14:15], v[14:15], v[20:21]
	v_pk_mul_f32 v[16:17], v[16:17], v[22:23]
	v_cvt_pk_bf16_f32 v14, v14, v15
	s_nop 0
	v_cvt_pk_bf16_f32 v15, v16, v17
	global_store_dwordx2 v[58:59], v[14:15], off offset:3584
	s_cbranch_scc1 .LBB0_711
